# phase_norm token loop: gain/scale/shift pieces of row chunks 1..3 loaded up front with the chunk-0 loads, counted waits
# speedup vs baseline: 1.0045x; 1.0045x over previous
.LBB0_1735:
	v_ashrrev_i32_e32 v3, 31, v2
	v_lshlrev_b64 v[24:25], 12, v[2:3]
	v_lshl_add_u64 v[42:43], v[14:15], 0, v[24:25]
	global_load_dwordx4 v[24:27], v[42:43], off
	global_load_dwordx4 v[28:31], v[42:43], off offset:1024
	global_load_dwordx4 v[32:35], v[42:43], off offset:2048
	s_nop 0
	global_load_dwordx4 v[42:45], v[42:43], off offset:3072
	v_add_u32_e32 v19, 0xffffe000, v2
	v_lshrrev_b32_e32 v19, 12, v19
	v_add_u32_e32 v19, 1, v19
	v_cmp_lt_i32_e32 vcc, s11, v2
	s_mul_i32 s0, s36, 5
	v_mov_b64_e32 v[46:47], s[20:21]
	v_cndmask_b32_e32 v19, 0, v19, vcc
	v_add_u32_e32 v19, s0, v19
	v_mad_u64_u32 v[54:55], s[0:1], v19, s29, v[46:47]
	v_lshlrev_b32_e32 v0, 2, v4
	v_lshl_add_u64 v[58:59], v[54:55], 0, s[96:97]
	v_lshl_add_u64 v[46:47], v[58:59], 0, v[0:1]
	global_load_dwordx4 v[46:49], v[46:47], off
	s_nop 0
	global_load_dwordx4 v[50:53], v[6:7], off
	v_lshl_add_u64 v[60:61], v[54:55], 0, v[0:1]
	global_load_dwordx4 v[54:57], v[60:61], off
	v_add_co_u32_e32 v146, vcc, v58, v18
	v_addc_co_u32_e32 v147, vcc, 0, v59, vcc
	v_add_co_u32_e32 v148, vcc, v58, v20
	v_addc_co_u32_e32 v149, vcc, 0, v59, vcc
	v_add_co_u32_e32 v150, vcc, v58, v22
	v_addc_co_u32_e32 v151, vcc, 0, v59, vcc
	global_load_dwordx4 v[86:89], v[8:9], off
	global_load_dwordx4 v[90:93], v[146:147], off
	global_load_dwordx4 v[94:97], v[60:61], off offset:1024
	global_load_dwordx4 v[98:101], v[10:11], off
	global_load_dwordx4 v[102:105], v[148:149], off
	global_load_dwordx4 v[106:109], v[60:61], off offset:2048
	global_load_dwordx4 v[110:113], v[12:13], off
	global_load_dwordx4 v[138:141], v[150:151], off
	global_load_dwordx4 v[142:145], v[60:61], off offset:3072
	v_mov_b32_e32 v23, v1
	s_mov_b64 s[0:1], 0
	s_mov_b32 s3, 0x43dc0000
	s_waitcnt vmcnt(15)
	v_mov_b32_e32 v68, v25
	s_waitcnt vmcnt(14)
	v_mov_b32_e32 v69, v29
	v_mov_b32_e32 v66, v24
	v_mov_b32_e32 v67, v28
	s_waitcnt vmcnt(13)
	v_mov_b32_e32 v76, v33
	s_waitcnt vmcnt(12)
	v_mov_b32_e32 v77, v43
	v_pk_mul_f32 v[68:69], v[68:69], v[68:69]
	v_mov_b32_e32 v62, v26
	v_mov_b32_e32 v63, v30
	v_mov_b32_e32 v74, v32
	v_mov_b32_e32 v75, v42
	v_pk_mul_f32 v[76:77], v[76:77], v[76:77]
	v_pk_fma_f32 v[66:67], v[66:67], v[66:67], v[68:69]
	v_mov_b32_e32 v64, v27
	v_mov_b32_e32 v65, v31
	v_mov_b32_e32 v70, v34
	v_mov_b32_e32 v71, v44
	v_pk_fma_f32 v[68:69], v[74:75], v[74:75], v[76:77]
	v_pk_fma_f32 v[62:63], v[62:63], v[62:63], v[66:67]
	v_mov_b32_e32 v72, v35
	v_mov_b32_e32 v73, v45
	v_pk_fma_f32 v[66:67], v[70:71], v[70:71], v[68:69]
	v_pk_fma_f32 v[62:63], v[64:65], v[64:65], v[62:63]
	v_pk_fma_f32 v[64:65], v[72:73], v[72:73], v[66:67]
	v_add_f32_e32 v0, v62, v63
	v_add_f32_e32 v0, v0, v64
	v_add_f32_e32 v0, v0, v65
	v_mov_b32_e32 v19, v0
	s_waitcnt vmcnt(11)
	v_pk_add_f32 v[48:49], v[48:49], 1.0 op_sel_hi:[1,0]
	v_pk_add_f32 v[46:47], v[46:47], 1.0 op_sel_hi:[1,0]
	v_lshlrev_b64 v[62:63], 11, v[2:3]
	v_lshl_add_u64 v[62:63], v[16:17], 0, v[62:63]
	s_waitcnt lgkmcnt(0)
	s_nop 1
	v_permlane32_swap_b32_e32 v19, v0
	v_add_f32_e32 v0, v0, v19
	v_mov_b32_e32 v19, v0
	s_waitcnt lgkmcnt(0)
	s_nop 1
	v_permlane16_swap_b32_e32 v19, v0
	v_add_f32_e32 v0, v0, v19
	s_waitcnt lgkmcnt(0)
	s_nop 1
	v_add_f32_dpp v0, v0, v0 row_ror:8 row_mask:0xf bank_mask:0xf
	ds_bpermute_b32 v19, v39, v0
	s_waitcnt lgkmcnt(0)
	v_add_f32_e32 v0, v0, v19
	s_waitcnt lgkmcnt(0)
	s_nop 1
	v_add_f32_dpp v0, v0, v0 quad_perm:[2,3,0,1] row_mask:0xf bank_mask:0xf
	v_mov_b32_e32 v19, v1
	v_lshl_add_u64 v[64:65], v[58:59], 0, v[18:19]
	s_waitcnt lgkmcnt(0)
	s_nop 1
	v_add_f32_dpp v0, v0, v0 quad_perm:[1,0,3,2] row_mask:0xf bank_mask:0xf
	v_fmamk_f32 v0, v0, 0x3a800000, v178
	v_mul_f32_e32 v21, 0x4b800000, v0
	v_cmp_gt_f32_e32 vcc, s64, v0
	s_nop 1
	v_cndmask_b32_e32 v0, v0, v21, vcc
	v_rsq_f32_e32 v0, v0
	v_mov_b32_e32 v21, v1
	v_mul_f32_e32 v19, 0x45800000, v0
	v_cndmask_b32_e32 v0, v0, v19, vcc
	v_pk_mul_f32 v[24:25], v[24:25], v[0:1] op_sel_hi:[1,0]
	v_pk_mul_f32 v[26:27], v[26:27], v[0:1] op_sel_hi:[1,0]
	s_waitcnt vmcnt(10)
	v_pk_mul_f32 v[24:25], v[50:51], v[24:25]
	v_pk_mul_f32 v[50:51], v[52:53], v[26:27]
	s_waitcnt vmcnt(9)
	v_pk_fma_f32 v[26:27], v[46:47], v[24:25], v[54:55]
	v_pk_fma_f32 v[24:25], v[48:49], v[50:51], v[56:57]
	v_cvt_pk_bf16_f32 v46, v26, v27
	v_cvt_pk_bf16_f32 v47, v24, v25
	global_store_dwordx2 v[62:63], v[46:47], off
	s_nop 0
	v_pk_mul_f32 v[28:29], v[28:29], v[0:1] op_sel_hi:[1,0]
	v_pk_mul_f32 v[30:31], v[30:31], v[0:1] op_sel_hi:[1,0]
	v_lshl_add_u64 v[64:65], v[58:59], 0, v[20:21]
	v_pk_mul_f32 v[32:33], v[32:33], v[0:1] op_sel_hi:[1,0]
	v_pk_mul_f32 v[34:35], v[34:35], v[0:1] op_sel_hi:[1,0]
	v_lshl_add_u64 v[58:59], v[58:59], 0, v[22:23]
	v_pk_mul_f32 v[44:45], v[44:45], v[0:1] op_sel_hi:[1,0]
	v_pk_mul_f32 v[42:43], v[42:43], v[0:1] op_sel_hi:[1,0]
	v_max_f32_e64 v0, |v24|, |v25|
	v_max3_f32 v0, |v26|, |v27|, v0
	s_waitcnt vmcnt(9)
	v_pk_mul_f32 v[28:29], v[28:29], v[86:87]
	s_waitcnt vmcnt(8)
	v_pk_add_f32 v[46:47], v[90:91], 1.0 op_sel_hi:[1,0]
	v_pk_mul_f32 v[48:49], v[30:31], v[88:89]
	v_pk_add_f32 v[50:51], v[92:93], 1.0 op_sel_hi:[1,0]
	s_waitcnt vmcnt(7)
	v_pk_fma_f32 v[30:31], v[28:29], v[46:47], v[94:95]
	v_pk_fma_f32 v[28:29], v[48:49], v[50:51], v[96:97]
	v_cvt_pk_bf16_f32 v46, v30, v31
	v_cvt_pk_bf16_f32 v47, v28, v29
	global_store_dwordx2 v[62:63], v[46:47], off offset:512
	s_nop 0
	v_max_f32_e64 v19, |v28|, |v29|
	v_max3_f32 v19, |v30|, |v31|, v19
	v_max3_f32 v0, v0, 0, v19
	s_waitcnt vmcnt(7)
	v_pk_mul_f32 v[32:33], v[32:33], v[98:99]
	s_waitcnt vmcnt(6)
	v_pk_add_f32 v[46:47], v[102:103], 1.0 op_sel_hi:[1,0]
	v_pk_mul_f32 v[48:49], v[34:35], v[100:101]
	v_pk_add_f32 v[50:51], v[104:105], 1.0 op_sel_hi:[1,0]
	s_waitcnt vmcnt(5)
	v_pk_fma_f32 v[34:35], v[32:33], v[46:47], v[106:107]
	v_pk_fma_f32 v[32:33], v[48:49], v[50:51], v[108:109]
	v_cvt_pk_bf16_f32 v46, v34, v35
	v_cvt_pk_bf16_f32 v47, v32, v33
	global_store_dwordx2 v[62:63], v[46:47], off offset:1024
	s_nop 0
	v_max_f32_e64 v19, |v32|, |v33|
	v_max3_f32 v19, |v34|, |v35|, v19
	s_waitcnt vmcnt(5)
	v_pk_mul_f32 v[44:45], v[44:45], v[112:113]
	s_waitcnt vmcnt(4)
	v_pk_add_f32 v[48:49], v[140:141], 1.0 op_sel_hi:[1,0]
	v_pk_mul_f32 v[42:43], v[42:43], v[110:111]
	v_pk_add_f32 v[46:47], v[138:139], 1.0 op_sel_hi:[1,0]
	s_waitcnt vmcnt(3)
	v_pk_fma_f32 v[44:45], v[44:45], v[48:49], v[144:145]
	v_pk_fma_f32 v[42:43], v[42:43], v[46:47], v[142:143]
	v_max_f32_e64 v21, |v44|, |v45|
	v_max3_f32 v21, |v42|, |v43|, v21
	v_max3_f32 v0, v0, v19, v21
	v_mov_b32_e32 v19, v0
	v_cvt_pk_bf16_f32 v48, v42, v43
	v_cvt_pk_bf16_f32 v49, v44, v45
	global_store_dwordx2 v[62:63], v[48:49], off offset:1536
	s_waitcnt lgkmcnt(0)
	s_nop 1
	v_permlane32_swap_b32_e32 v19, v0
	v_max_f32_e32 v0, v0, v19
	v_mov_b32_e32 v19, v0
	s_add_u32 s0, s90, s0
	v_lshlrev_b64 v[46:47], 10, v[2:3]
	s_addc_u32 s1, s91, s1
	v_lshl_add_u64 v[46:47], s[0:1], 0, v[46:47]
	s_waitcnt lgkmcnt(0)
	s_nop 1
	v_permlane16_swap_b32_e32 v19, v0
	v_max_f32_e32 v0, v0, v19
	v_lshl_add_u64 v[46:47], v[46:47], 0, v[4:5]
	s_mov_b64 s[0:1], 0x341fd700
	v_lshl_add_u64 v[48:49], v[46:47], 0, s[0:1]
	v_mov_b32_e32 v21, v1
	s_waitcnt lgkmcnt(0)
	s_nop 1
	v_max_f32_dpp v0, v0, v0 row_ror:8 row_mask:0xf bank_mask:0xf
	ds_bpermute_b32 v19, v39, v0
	v_mov_b32_e32 v50, v1
	v_mov_b32_e32 v51, v1
	s_waitcnt lgkmcnt(0)
	v_max_f32_e32 v19, v19, v19
	v_max_f32_e32 v0, v0, v19
	s_waitcnt lgkmcnt(0)
	s_nop 1
	v_max_f32_dpp v0, v0, v0 quad_perm:[2,3,0,1] row_mask:0xf bank_mask:0xf
	s_waitcnt lgkmcnt(0)
	s_nop 1
	v_max_f32_dpp v0, v0, v0 quad_perm:[1,0,3,2] row_mask:0xf bank_mask:0xf
	v_div_scale_f32 v19, s[0:1], v0, v0, s3
	v_rcp_f32_e32 v52, v19
	s_mov_b32 s0, 0x341fd000
	v_add_co_u32_e32 v46, vcc, s0, v46
	v_fma_f32 v54, -v19, v52, 1.0
	s_nop 0
	v_addc_co_u32_e32 v47, vcc, 0, v47, vcc
	v_div_scale_f32 v53, vcc, s3, v0, s3
	v_fmac_f32_e32 v52, v54, v52
	v_mul_f32_e32 v54, v53, v52
	v_fma_f32 v55, -v19, v54, v53
	v_fmac_f32_e32 v54, v55, v52
	v_fma_f32 v19, -v19, v54, v53
	v_div_fmas_f32 v19, v19, v52, v54
	v_div_fixup_f32 v19, v19, v0, s3
	v_cmp_lt_f32_e64 s[0:1], 0, v0
	s_nop 1
	v_cndmask_b32_e64 v19, 1.0, v19, s[0:1]
	v_mul_f32_e32 v26, v26, v19
	v_mul_f32_e32 v27, v27, v19
	v_mul_f32_e32 v30, v30, v19
	v_mul_f32_e32 v31, v31, v19
	v_cvt_pk_fp8_f32 v21, v26, v27
	v_mul_f32_e32 v34, v34, v19
	v_mul_f32_e32 v35, v35, v19
	v_cvt_pk_fp8_f32 v23, v30, v31
	v_mul_f32_e32 v42, v42, v19
	v_mul_f32_e32 v43, v43, v19
	v_cvt_pk_fp8_f32 v50, v34, v35
	v_mul_f32_e32 v24, v24, v19
	v_mul_f32_e32 v25, v25, v19
	v_cvt_pk_fp8_f32 v51, v42, v43
	v_mul_f32_e32 v28, v28, v19
	v_mul_f32_e32 v29, v29, v19
	v_cvt_pk_fp8_f32 v21, v24, v25 op_sel:[0,0,1]
	v_mul_f32_e32 v32, v32, v19
	v_mul_f32_e32 v33, v33, v19
	v_cvt_pk_fp8_f32 v23, v28, v29 op_sel:[0,0,1]
	v_mul_f32_e32 v44, v44, v19
	v_mul_f32_e32 v19, v45, v19
	v_cvt_pk_fp8_f32 v50, v32, v33 op_sel:[0,0,1]
	v_cvt_pk_fp8_f32 v51, v44, v19 op_sel:[0,0,1]
	global_store_dword v[46:47], v21, off offset:1792
	global_store_dword v[48:49], v23, off offset:256
	global_store_dword v[48:49], v50, off offset:512
	global_store_dword v[48:49], v51, off offset:768
	s_and_saveexec_b64 s[22:23], s[40:41]
	s_cbranch_execz .LBB0_1734
	v_div_scale_f32 v19, s[34:35], s3, s3, v0
	v_rcp_f32_e32 v21, v19
	v_div_scale_f32 v23, vcc, v0, s3, v0
	v_fma_f32 v24, -v19, v21, 1.0
	v_fmac_f32_e32 v21, v24, v21
	v_mul_f32_e32 v24, v23, v21
	v_fma_f32 v25, -v19, v24, v23
	v_fmac_f32_e32 v24, v25, v21
	v_fma_f32 v19, -v19, v24, v23
	v_div_fmas_f32 v19, v19, v21, v24
	v_div_fixup_f32 v0, v19, s3, v0
	v_cndmask_b32_e64 v0, 1.0, v0, s[0:1]
	s_mov_b64 s[0:1], 0
	s_add_u32 s0, s90, s0
	s_addc_u32 s1, s91, s1
	v_lshl_add_u64 v[24:25], v[2:3], 2, s[0:1]
	v_add_co_u32_e32 v24, vcc, 0x359fd000, v24
	s_nop 1
	v_addc_co_u32_e32 v25, vcc, 0, v25, vcc
	global_store_dword v[24:25], v0, off offset:1792
	s_branch .LBB0_1734
